# baseline (speedup 1.0000x reference)
; __device__ __forceinline__ float bf2f(u16 h) { return __uint_as_float(((unsigned)h) << 16); }
; template <int DUMMY>
; __device__ void ssd_item(const Params& p, int item) {
;     ...
;     {
; #pragma unroll
;       for (int i = 0; i < 2; ++i) {
;         int idx = tid + i * NT;
;         *(i32x4*)(Bs + (idx >> 4) * 136 + (idx & 15) * 8) = rBs[i];
;         *(i32x4*)(Cs + (idx >> 4) * 136 + (idx & 15) * 8) = rCs[i];
;         int c8 = idx >> 6, ll = idx & 63;
; #pragma unroll
;         for (int e = 0; e < 4; ++e) {
;           unsigned u = (unsigned)rBT[i][e];
;           BTs[(c8 * 8 + 2 * e) * 72 + ll] = (u16)(u & 0xffffu);
;           BTs[(c8 * 8 + 2 * e + 1) * 72 + ll] = (u16)(u >> 16);
;         }
;       }
;       {
;         float w0 = cwX[0 * 32 + chg], w1 = cwX[1 * 32 + chg], w2 = cwX[2 * 32 + chg], w3 = cwX[3 * 32 + chg], bx = cwX[4 * 32 + chg];
;         float raw[7];
; #pragma unroll
;         for (int i = 0; i < 7; ++i) raw[i] = bf2f(rX[i]);
;         const float cs63 = cs[63];
;         float4 dt4 = *(const float4*)(dv + l0), cs4 = *(const float4*)(cs + l0);
;         float dts[4] = {dt4.x, dt4.y, dt4.z, dt4.w}, css[4] = {cs4.x, cs4.y, cs4.z, cs4.w};
.LBB0_1033:
	s_bfe_i32 s3, s76, 0x10000
	s_and_b32 s3, s3, 0x15800
	v_lshl_or_b32 v32, v59, 1, s3
	s_lshl_b32 s31, s97, 8
	ds_write_b128 v116, v[20:23] offset:17408
	v_lshl_add_u32 v20, v146, 1, v32
	s_add_i32 s52, s31, 0x1e200
	ds_write_b128 v20, v[16:19]
	ds_write_b128 v117, v[24:27] offset:17408
	v_lshl_add_u32 v251, v147, 1, v32
	ds_write_b128 v251, v[28:31]
	v_mov_b32_e32 v250, s52
	ds_read2_b32 v[16:17], v115 offset1:32
	ds_read2_b32 v[18:19], v115 offset0:64 offset1:96
	ds_read_b32 v20, v115 offset:512
	ds_read_b32 v21, v250 offset:252
	ds_write_b16 v52, v12 offset:34816
	ds_write_b16_d16_hi v52, v12 offset:34960
	ds_write_b16 v52, v13 offset:35104
	ds_write_b16_d16_hi v52, v13 offset:35248
	ds_write_b16 v52, v14 offset:35392
	ds_write_b16_d16_hi v52, v14 offset:35536
	ds_write_b16 v52, v15 offset:35680
	ds_write_b16_d16_hi v52, v15 offset:35824
	ds_write_b16 v54, v8 offset:34816
	ds_write_b16_d16_hi v54, v8 offset:34960
	ds_write_b16 v54, v9 offset:35104
	ds_write_b16_d16_hi v54, v9 offset:35248
	ds_write_b16 v54, v10 offset:35392
	ds_write_b16_d16_hi v54, v10 offset:35536
	ds_write_b16 v54, v11 offset:35680
	ds_write_b16_d16_hi v54, v11 offset:35824
	v_and_b32_e32 v23, 0xffff0000, v173
	v_lshlrev_b32_e32 v22, 16, v173
	v_and_b32_e32 v13, 0xffff0000, v171
	v_lshlrev_b32_e32 v12, 16, v171
	v_add_u32_e32 v31, s31, v114
	v_lshlrev_b32_e32 v24, 16, v101
	s_waitcnt lgkmcnt(15)
	v_pk_fma_f32 v[14:15], v[16:17], v[12:13], v[20:21] op_sel_hi:[0,1,0]
	v_mov_b32_e32 v30, v17
	v_pk_mov_b32 v[12:13], v[12:13], v[22:23] op_sel:[1,0]
	v_lshlrev_b32_e32 v26, 16, v100
	v_pk_fma_f32 v[12:13], v[30:31], v[12:13], v[14:15] op_sel_hi:[0,1,1]
	v_mov_b32_e32 v14, v22
	v_mov_b32_e32 v15, v24
	v_pk_fma_f32 v[12:13], v[18:19], v[14:15], v[12:13] op_sel_hi:[0,1,1]
	v_mov_b32_e32 v32, v19
	v_mov_b32_e32 v14, v24
	v_mov_b32_e32 v15, v26
	v_pk_fma_f32 v[12:13], v[32:33], v[14:15], v[12:13] op_sel_hi:[0,1,1]
	v_and_b32_e32 v25, 0xffff0000, v101
	v_mul_f32_e32 v14, 0xbfb8aa3b, v12
	v_mul_f32_e32 v15, 0xbfb8aa3b, v13
	v_pk_fma_f32 v[16:17], v[16:17], v[22:23], v[20:21] op_sel_hi:[0,1,0]
	v_and_b32_e32 v27, 0xffff0000, v100
	v_exp_f32_e32 v14, v14
	v_exp_f32_e32 v15, v15
	v_pk_fma_f32 v[16:17], v[30:31], v[24:25], v[16:17] op_sel_hi:[0,1,1]
	v_and_b32_e32 v29, 0xffff0000, v42
	v_lshlrev_b32_e32 v28, 16, v42
	v_pk_fma_f32 v[16:17], v[18:19], v[26:27], v[16:17] op_sel_hi:[0,1,1]
	v_pk_fma_f32 v[16:17], v[32:33], v[28:29], v[16:17] op_sel_hi:[0,1,1]
	v_lshl_add_u32 v8, v50, 2, s52
	v_mul_f32_e32 v18, 0xbfb8aa3b, v16
	v_mul_f32_e32 v19, 0xbfb8aa3b, v17
	ds_read_b128 v[8:11], v8
	v_add_f32_e32 v14, 1.0, v14
	v_add_f32_e32 v15, 1.0, v15
	v_exp_f32_e32 v18, v18
	v_exp_f32_e32 v19, v19
	v_rcp_f32_e32 v14, v14
	v_rcp_f32_e32 v15, v15
	v_add_f32_e32 v18, 1.0, v18
	v_add_f32_e32 v19, 1.0, v19
	v_rcp_f32_e32 v18, v18
	v_pk_mul_f32 v[34:35], v[12:13], v[14:15]
	ds_read_b128 v[12:15], v31
	s_waitcnt lgkmcnt(1)
	v_sub_f32_e32 v8, v21, v8
	v_sub_f32_e32 v9, v21, v9
	v_sub_f32_e32 v10, v21, v10
	v_rcp_f32_e32 v19, v19
	v_sub_f32_e32 v11, v21, v11
	v_mul_f32_e32 v8, 0x3fb8aa3b, v8
	v_mul_f32_e32 v9, 0x3fb8aa3b, v9
	v_mul_f32_e32 v10, 0x3fb8aa3b, v10
	v_mul_f32_e32 v11, 0x3fb8aa3b, v11
	v_exp_f32_e32 v8, v8
	v_exp_f32_e32 v9, v9
	v_exp_f32_e32 v10, v10
	v_exp_f32_e32 v11, v11
	s_and_b32 s30, s76, 1
	s_cmp_eq_u32 s30, 0
	s_mov_b32 s30, 0xf400
	v_pk_mul_f32 v[16:17], v[16:17], v[18:19]
	s_cselect_b32 s77, s30, 0x1ae00
	s_waitcnt lgkmcnt(0)
; template <int DUMMY>
; __device__ void ssd_item(const Params& p, int item) {
;     ...
;         *(i32x2*)(xT + chg * 72 + l0) = i32x2{(int)pack2(vx[0], vx[1]), (int)pack2(vx[2], vx[3])};
;         *(i32x2*)(xdT + chg * 72 + l0) = i32x2{(int)pack2(vd[0], vd[1]), (int)pack2(vd[2], vd[3])};
;         *(i32x2*)(xwT + chg * 72 + l0) = i32x2{(int)pack2(vw[0], vw[1]), (int)pack2(vw[2], vw[3])};
;       }
;     }
; #pragma unroll
;     for (int j = 0; j < 2; ++j)
; #pragma unroll
;       for (int r = 0; r < 4; ++r) Sb[(pf * 16 + g4 * 4 + r) * 136 + (nf0 + j) * 16 + fr] = f2bf(accS[j][r]);
; #pragma unroll
;     for (int r = 0; r < 4; ++r) zcur[r] = znext[r];
;     if (c > 1) {
;       const size_t yi = (tb + (c - 2) * 64 + (tid >> 3)) * 4096 + h * 64 + ph * 32 + (tid & 7) * 4;
;       *(i32x2*)(zyo + (yi & omask)) = ypend;
;     }
;     if (c + 1 < 128) {
;       load_raw(c + 1);
;       const size_t zn = zbase + (size_t)64 * 4096;
; #pragma unroll
;       for (int r = 0; r < 4; ++r) znext[r] = zy[zn + (size_t)r * 4096];
;       if (wid == 0) {
;         float dt_use = dt_n;
;         if (c + 2 < 128) dt_n = dtb[(tb + (c + 2) * 64 + lane) * 64 + h];
;         write_cs(dt_use, nxt3);
	v_pk_mul_f32 v[12:13], v[12:13], v[34:35]
	v_pk_mul_f32 v[14:15], v[14:15], v[16:17]
	s_mov_b32 s30, 0xd000
	v_pk_mul_f32 v[8:9], v[8:9], v[12:13]
	v_pk_mul_f32 v[10:11], v[14:15], v[10:11]
	s_cselect_b32 s53, s30, 0x19c00
	v_cvt_pk_bf16_f32 v19, v16, v17
	v_lshlrev_b32_e32 v16, 1, v143
	s_cselect_b32 s78, 0x12a00, s93
	v_cvt_pk_bf16_f32 v18, v34, v35
	v_add3_u32 v17, s77, v16, v144
	v_cvt_pk_bf16_f32 v12, v12, v13
	v_cvt_pk_bf16_f32 v13, v14, v15
	v_add3_u32 v14, s53, v16, v144
	v_cvt_pk_bf16_f32 v8, v8, v9
	v_cvt_pk_bf16_f32 v9, v10, v11
	ds_write_b64 v17, v[18:19]
	ds_write_b64 v14, v[12:13]
	ds_write_b64 v113, v[8:9] offset:57856
	v_lshl_or_b32 v8, v56, 1, s78
	v_cvt_pk_bf16_f32 v9, v4, s0
	v_add3_u32 v10, v8, v55, v159
	ds_write_b16 v10, v9
	v_cvt_pk_bf16_f32 v9, v5, s0
	ds_write_b16 v10, v9 offset:272
	v_cvt_pk_bf16_f32 v9, v6, s0
	ds_write_b16 v10, v9 offset:544
	v_cvt_pk_bf16_f32 v9, v7, s0
	ds_write_b16 v10, v9 offset:816
	v_cvt_pk_bf16_f32 v9, v0, s0
	v_add3_u32 v8, v8, v153, v159
	ds_write_b16 v8, v9
	v_cvt_pk_bf16_f32 v9, v1, s0
	ds_write_b16 v8, v9 offset:272
	v_cvt_pk_bf16_f32 v9, v2, s0
	ds_write_b16 v8, v9 offset:544
	v_cvt_pk_bf16_f32 v9, v3, s0
	ds_write_b16 v8, v9 offset:816
	v_lshl_add_u64 v[8:9], s[42:43], 0, v[98:99]
	global_store_dwordx2 v[8:9], v[82:83], off
	v_lshl_add_u64 v[8:9], v[78:79], 0, s[70:71]
	s_mov_b32 s30, 0xc0000
	v_add_co_u32_e32 v8, vcc, s30, v8
	v_add_u32_e32 v40, -6, v86
	s_nop 0
	v_addc_co_u32_e32 v9, vcc, 0, v9, vcc
	global_load_dwordx4 v[20:23], v[8:9], off
	global_load_dwordx4 v[16:19], v[8:9], off offset:2048
	v_lshl_add_u64 v[8:9], v[90:91], 0, s[70:71]
	global_load_dwordx4 v[12:15], v[8:9], off
	v_lshl_add_u64 v[8:9], v[80:81], 0, s[70:71]
	v_add_co_u32_e32 v8, vcc, 0xc0000, v8
	v_mov_b32_e32 v172, 0
	s_nop 0
	v_addc_co_u32_e32 v9, vcc, 0, v9, vcc
	global_load_dwordx4 v[24:27], v[8:9], off
	global_load_dwordx4 v[28:31], v[8:9], off offset:2048
	v_lshl_add_u64 v[8:9], v[88:89], 0, s[70:71]
	global_load_dwordx4 v[8:11], v[8:9], off
	v_lshl_add_u64 v[32:33], s[64:65], 0, v[40:41]
	v_mad_u64_u32 v[34:35], s[72:73], v32, s86, v[66:67]
	v_mad_i32_i24 v35, v33, s86, v35
	global_load_ushort v171, v[34:35], off
	v_add_co_u32_e32 v34, vcc, 0x3000, v34
	s_nop 1
	v_addc_co_u32_e32 v35, vcc, 0, v35, vcc
	global_load_ushort v172, v[34:35], off
	v_add_co_u32_e32 v34, vcc, 0x3000, v34
	s_nop 1
	v_addc_co_u32_e32 v35, vcc, 0, v35, vcc
	global_load_ushort v174, v[34:35], off
	v_add_co_u32_e32 v34, vcc, 0x3000, v34
	s_nop 1
	v_addc_co_u32_e32 v35, vcc, 0, v35, vcc
	global_load_ushort v173, v[34:35], off
	v_add_co_u32_e32 v34, vcc, 0x3000, v34
	s_nop 1
	v_addc_co_u32_e32 v35, vcc, 0, v35, vcc
	global_load_ushort v175, v[34:35], off
	v_add_co_u32_e32 v34, vcc, 0x3000, v34
	s_nop 1
	v_addc_co_u32_e32 v35, vcc, 0, v35, vcc
	global_load_ushort v176, v[34:35], off
	v_add_co_u32_e32 v34, vcc, 0x3000, v34
	s_nop 1
	v_addc_co_u32_e32 v35, vcc, 0, v35, vcc
	global_load_ushort v40, v[34:35], off
	v_lshl_add_u64 v[32:33], s[42:43], 0, v[84:85]
	v_add_co_u32_e32 v34, vcc, 0xb280000, v32
	s_add_i32 s30, s97, 1
	s_nop 0
	v_addc_co_u32_e32 v35, vcc, 0, v33, vcc
	global_load_ushort v170, v[34:35], off
	v_add_co_u32_e32 v34, vcc, 0xb282000, v32
	s_cmp_lg_u32 s97, 2
	s_nop 0
	v_addc_co_u32_e32 v35, vcc, 0, v33, vcc
	global_load_ushort v169, v[34:35], off
	v_add_co_u32_e32 v34, vcc, 0xb284000, v32
	s_cselect_b32 s97, s30, 0
	s_nop 0
	v_addc_co_u32_e32 v35, vcc, 0, v33, vcc
	v_add_co_u32_e32 v32, vcc, 0xb286000, v32
	global_load_ushort v168, v[34:35], off
	s_nop 0
	v_addc_co_u32_e32 v33, vcc, 0, v33, vcc
	global_load_ushort v49, v[32:33], off
	s_and_saveexec_b64 s[30:31], s[4:5]
	s_cbranch_execz .LBB0_1049
	v_lshl_add_u64 v[32:33], s[42:43], 0, v[92:93]
	global_load_dword v255, v[32:33], off
	v_mul_f32_e64 v33, v118, -v120
	s_nop 1
	v_mov_b32_dpp v33, v33 row_shr:1 row_mask:0xf bank_mask:0xf bound_ctrl:1
	v_fma_f32 v33, v118, -v120, v33
	s_nop 1
	v_add_f32_dpp v33, v33, v33 row_shr:2 row_mask:0xf bank_mask:0xf bound_ctrl:1
	s_nop 1
	v_add_f32_dpp v33, v33, v33 row_shr:4 row_mask:0xf bank_mask:0xf bound_ctrl:1
	s_nop 1
	v_add_f32_dpp v33, v33, v33 row_shr:8 row_mask:0xf bank_mask:0xf bound_ctrl:1
	s_nop 0
	v_readlane_b32 s72, v33, 15
	v_readlane_b32 s73, v33, 31
	v_readlane_b32 vcc_lo, v33, 47
	v_mov_b32_e32 v34, s72
	v_mov_b32_e32 v35, s73
	v_cndmask_b32_e64 v34, v34, 0, s[26:27]
	v_cndmask_b32_e64 v35, 0, v35, s[24:25]
	v_add_f32_e32 v34, v34, v35
	v_mov_b32_e32 v35, vcc_lo
	v_cndmask_b32_e64 v35, 0, v35, s[22:23]
	v_add_f32_e32 v34, v35, v34
	v_add_f32_e32 v33, v33, v34
	v_lshl_or_b32 v34, s97, 8, v135
	v_add_u32_e32 v35, 0x1e200, v34
	ds_write_b32 v35, v33
	v_add_u32_e32 v33, 0x1e500, v34
	ds_write_b32 v33, v118
